# G1 conv L2-norm sums by DPP row operations instead of four dependent ds_bpermute round trips per token, on top of the v-split
# speedup vs baseline: 1.0079x; 1.0016x over previous
.Lg1a_norm:
	s_waitcnt vmcnt(11)
	v_lshlrev_b32_e32 v78, 16, v0
	v_and_b32_e32 v79, 0xffff0000, v0
	v_lshlrev_b32_e32 v102, 16, v4
	v_and_b32_e32 v103, 0xffff0000, v4
	v_lshlrev_b32_e32 v90, 16, v8
	v_and_b32_e32 v91, 0xffff0000, v8
	v_lshlrev_b32_e32 v100, 16, v12
	v_and_b32_e32 v101, 0xffff0000, v12
	v_lshlrev_b32_e32 v104, 16, v5
	v_and_b32_e32 v105, 0xffff0000, v5
	v_lshlrev_b32_e32 v86, 16, v9
	v_and_b32_e32 v87, 0xffff0000, v9
	v_lshlrev_b32_e32 v98, 16, v13
	v_and_b32_e32 v99, 0xffff0000, v13
	v_lshlrev_b32_e32 v106, 16, v6
	v_and_b32_e32 v107, 0xffff0000, v6
	v_lshlrev_b32_e32 v88, 16, v10
	v_and_b32_e32 v89, 0xffff0000, v10
	v_lshlrev_b32_e32 v96, 16, v14
	v_and_b32_e32 v97, 0xffff0000, v14
	v_lshlrev_b32_e32 v108, 16, v7
	v_and_b32_e32 v109, 0xffff0000, v7
	v_lshlrev_b32_e32 v92, 16, v11
	v_and_b32_e32 v93, 0xffff0000, v11
	v_lshlrev_b32_e32 v94, 16, v15
	v_and_b32_e32 v95, 0xffff0000, v15
	s_movk_i32 s8, 0x80
	v_cmp_gt_u32_e64 s[42:43], s8, v210
	v_cmp_ne_u32_e64 s[40:41], 2, v188
	v_pk_fma_f32 v[78:79], v[58:59], v[78:79], 0 op_sel_hi:[1,1,0]
	v_cndmask_b32_e64 v44, 1.0, v205, s[42:43]
	v_pk_fma_f32 v[78:79], v[62:63], v[102:103], v[78:79]
	s_nop 0
	v_pk_fma_f32 v[78:79], v[70:71], v[90:91], v[78:79]
	s_nop 0
	v_pk_fma_f32 v[78:79], v[74:75], v[100:101], v[78:79]
	s_nop 0
	v_mul_f32_e32 v80, 0xbfb8aa3b, v78
	v_mul_f32_e32 v81, 0xbfb8aa3b, v79
	v_exp_f32_e32 v80, v80
	v_exp_f32_e32 v81, v81
	v_add_f32_e32 v80, 1.0, v80
	v_add_f32_e32 v81, 1.0, v81
	v_rcp_f32_e32 v80, v80
	v_rcp_f32_e32 v81, v81
	s_nop 0
	v_pk_mul_f32 v[78:79], v[78:79], v[80:81]
	v_lshlrev_b32_e32 v80, 16, v1
	v_and_b32_e32 v81, 0xffff0000, v1
	v_pk_fma_f32 v[80:81], v[60:61], v[80:81], 0 op_sel_hi:[1,1,0]
	s_nop 0
	v_pk_fma_f32 v[80:81], v[64:65], v[104:105], v[80:81]
	s_nop 0
	v_pk_fma_f32 v[80:81], v[72:73], v[86:87], v[80:81]
	s_nop 0
	v_pk_fma_f32 v[80:81], v[76:77], v[98:99], v[80:81]
	s_nop 0
	v_mul_f32_e32 v82, 0xbfb8aa3b, v80
	v_mul_f32_e32 v83, 0xbfb8aa3b, v81
	v_exp_f32_e32 v82, v82
	v_exp_f32_e32 v83, v83
	v_add_f32_e32 v82, 1.0, v82
	v_add_f32_e32 v83, 1.0, v83
	v_rcp_f32_e32 v82, v82
	v_rcp_f32_e32 v83, v83
	s_nop 0
	v_pk_mul_f32 v[80:81], v[80:81], v[82:83]
	v_lshlrev_b32_e32 v82, 16, v2
	v_and_b32_e32 v83, 0xffff0000, v2
	v_pk_fma_f32 v[82:83], v[46:47], v[82:83], 0 op_sel_hi:[1,1,0]
	s_nop 0
	v_pk_fma_f32 v[82:83], v[50:51], v[106:107], v[82:83]
	s_nop 0
	v_pk_fma_f32 v[82:83], v[54:55], v[88:89], v[82:83]
	s_nop 0
	v_pk_fma_f32 v[82:83], v[66:67], v[96:97], v[82:83]
	s_nop 0
	v_mul_f32_e32 v84, 0xbfb8aa3b, v82
	v_mul_f32_e32 v85, 0xbfb8aa3b, v83
	v_exp_f32_e32 v84, v84
	v_exp_f32_e32 v85, v85
	v_add_f32_e32 v84, 1.0, v84
	v_add_f32_e32 v85, 1.0, v85
	v_rcp_f32_e32 v84, v84
	v_rcp_f32_e32 v85, v85
	s_nop 0
	v_pk_mul_f32 v[82:83], v[82:83], v[84:85]
	v_lshlrev_b32_e32 v84, 16, v3
	v_and_b32_e32 v85, 0xffff0000, v3
	v_pk_fma_f32 v[84:85], v[48:49], v[84:85], 0 op_sel_hi:[1,1,0]
	s_nop 0
	v_pk_fma_f32 v[84:85], v[52:53], v[108:109], v[84:85]
	s_nop 0
	v_pk_fma_f32 v[84:85], v[56:57], v[92:93], v[84:85]
	s_nop 0
	v_pk_fma_f32 v[84:85], v[68:69], v[94:95], v[84:85]
	s_nop 0
	v_mul_f32_e32 v110, 0xbfb8aa3b, v84
	v_mul_f32_e32 v111, 0xbfb8aa3b, v85
	v_exp_f32_e32 v110, v110
	v_exp_f32_e32 v111, v111
	v_add_f32_e32 v110, 1.0, v110
	v_add_f32_e32 v111, 1.0, v111
	v_rcp_f32_e32 v110, v110
	v_rcp_f32_e32 v111, v111
	s_nop 0
	v_pk_mul_f32 v[84:85], v[84:85], v[110:111]
	s_and_saveexec_b64 s[8:9], s[40:41]
	s_cbranch_execz .LBB0_293
	v_pk_mul_f32 v[110:111], v[78:79], v[78:79]
	v_pk_mul_f32 v[112:113], v[80:81], v[80:81]
	v_add_f32_e32 v110, v110, v111
	v_add_f32_e32 v110, v112, v110
	v_pk_mul_f32 v[114:115], v[82:83], v[82:83]
	v_add_f32_e32 v110, v113, v110
	v_add_f32_e32 v110, v114, v110
	v_pk_mul_f32 v[116:117], v[84:85], v[84:85]
	v_add_f32_e32 v110, v115, v110
	v_add_f32_e32 v110, v116, v110
	v_add_f32_e32 v110, v117, v110
	s_nop 1
	v_add_f32_dpp v110, v110, v110 quad_perm:[1,0,3,2] row_mask:0xf bank_mask:0xf
	s_nop 1
	v_add_f32_dpp v110, v110, v110 quad_perm:[2,3,0,1] row_mask:0xf bank_mask:0xf
	s_nop 1
	v_add_f32_dpp v110, v110, v110 row_half_mirror row_mask:0xf bank_mask:0xf
	s_nop 1
	v_add_f32_dpp v110, v110, v110 row_mirror row_mask:0xf bank_mask:0xf
	v_add_f32_e32 v110, 0x358637bd, v110
	v_rsq_f32_e32 v110, v110
	s_nop 0
	v_mul_f32_e32 v110, v44, v110
	v_pk_mul_f32 v[78:79], v[78:79], v[110:111] op_sel_hi:[1,0]
	v_pk_mul_f32 v[80:81], v[80:81], v[110:111] op_sel_hi:[1,0]
	v_pk_mul_f32 v[82:83], v[82:83], v[110:111] op_sel_hi:[1,0]
	v_pk_mul_f32 v[84:85], v[84:85], v[110:111] op_sel_hi:[1,0]

.Lg1a_t4:
	v_pk_fma_f32 v[94:95], v[58:59], v[138:139], 0 op_sel_hi:[1,1,0]
	v_lshlrev_b32_e32 v152, 16, v28
	v_and_b32_e32 v150, 0xffff0000, v28
	v_pk_fma_f32 v[94:95], v[62:63], v[140:141], v[94:95]
	v_mov_b32_e32 v156, v152
	v_pk_fma_f32 v[94:95], v[70:71], v[136:137], v[94:95]
	v_mov_b32_e32 v157, v150
	v_pk_fma_f32 v[94:95], v[74:75], v[156:157], v[94:95]
	v_lshlrev_b32_e32 v148, 16, v29
	v_mul_f32_e32 v96, 0xbfb8aa3b, v94
	v_mul_f32_e32 v97, 0xbfb8aa3b, v95
	v_exp_f32_e32 v96, v96
	v_exp_f32_e32 v97, v97
	v_and_b32_e32 v146, 0xffff0000, v29
	v_mov_b32_e32 v158, v148
	v_add_f32_e32 v96, 1.0, v96
	v_add_f32_e32 v97, 1.0, v97
	v_rcp_f32_e32 v96, v96
	v_rcp_f32_e32 v97, v97
	v_mov_b32_e32 v159, v146
	v_and_b32_e32 v145, 0xffff0000, v30
	v_lshlrev_b32_e32 v144, 16, v30
	v_pk_mul_f32 v[96:97], v[94:95], v[96:97]
	v_pk_fma_f32 v[94:95], v[60:61], v[124:125], 0 op_sel_hi:[1,1,0]
	v_and_b32_e32 v143, 0xffff0000, v31
	v_pk_fma_f32 v[94:95], v[64:65], v[130:131], v[94:95]
	v_lshlrev_b32_e32 v142, 16, v31
	v_pk_fma_f32 v[94:95], v[72:73], v[134:135], v[94:95]
	v_lshlrev_b32_e32 v153, 16, v32
	v_pk_fma_f32 v[94:95], v[76:77], v[158:159], v[94:95]
	v_and_b32_e32 v151, 0xffff0000, v32
	v_mul_f32_e32 v98, 0xbfb8aa3b, v94
	v_mul_f32_e32 v99, 0xbfb8aa3b, v95
	v_exp_f32_e32 v98, v98
	v_exp_f32_e32 v99, v99
	v_lshlrev_b32_e32 v149, 16, v33
	v_and_b32_e32 v147, 0xffff0000, v33
	v_add_f32_e32 v98, 1.0, v98
	v_add_f32_e32 v99, 1.0, v99
	v_rcp_f32_e32 v98, v98
	v_rcp_f32_e32 v99, v99
	s_nop 0
	v_pk_mul_f32 v[94:95], v[94:95], v[98:99]
	v_pk_fma_f32 v[98:99], v[46:47], v[118:119], 0 op_sel_hi:[1,1,0]
	s_nop 0
	v_pk_fma_f32 v[98:99], v[50:51], v[120:121], v[98:99]
	s_nop 0
	v_pk_fma_f32 v[98:99], v[54:55], v[132:133], v[98:99]
	s_nop 0
	v_pk_fma_f32 v[98:99], v[66:67], v[144:145], v[98:99]
	s_nop 0
	v_mul_f32_e32 v100, 0xbfb8aa3b, v98
	v_mul_f32_e32 v101, 0xbfb8aa3b, v99
	v_exp_f32_e32 v100, v100
	v_exp_f32_e32 v101, v101
	v_add_f32_e32 v100, 1.0, v100
	v_add_f32_e32 v101, 1.0, v101
	v_rcp_f32_e32 v100, v100
	v_rcp_f32_e32 v101, v101
	s_nop 0
	v_pk_mul_f32 v[98:99], v[98:99], v[100:101]
	v_pk_fma_f32 v[100:101], v[48:49], v[110:111], 0 op_sel_hi:[1,1,0]
	s_nop 0
	v_pk_fma_f32 v[100:101], v[52:53], v[112:113], v[100:101]
	s_nop 0
	v_pk_fma_f32 v[100:101], v[56:57], v[122:123], v[100:101]
	s_nop 0
	v_pk_fma_f32 v[100:101], v[68:69], v[142:143], v[100:101]
	s_nop 0
	v_mul_f32_e32 v110, 0xbfb8aa3b, v100
	v_mul_f32_e32 v111, 0xbfb8aa3b, v101
	v_exp_f32_e32 v110, v110
	v_exp_f32_e32 v111, v111
	v_add_f32_e32 v110, 1.0, v110
	v_add_f32_e32 v111, 1.0, v111
	v_rcp_f32_e32 v110, v110
	v_rcp_f32_e32 v111, v111
	s_nop 0
	v_pk_mul_f32 v[100:101], v[100:101], v[110:111]
	s_and_saveexec_b64 s[8:9], s[40:41]
	s_cbranch_execz .LBB0_301
	v_pk_mul_f32 v[110:111], v[96:97], v[96:97]
	v_pk_mul_f32 v[118:119], v[94:95], v[94:95]
	v_add_f32_e32 v110, v110, v111
	v_add_f32_e32 v110, v118, v110
	v_pk_mul_f32 v[124:125], v[98:99], v[98:99]
	v_add_f32_e32 v110, v119, v110
	v_add_f32_e32 v110, v124, v110
	v_pk_mul_f32 v[138:139], v[100:101], v[100:101]
	v_add_f32_e32 v110, v125, v110
	v_add_f32_e32 v110, v138, v110
	v_add_f32_e32 v110, v139, v110
	s_nop 1
	v_add_f32_dpp v110, v110, v110 quad_perm:[1,0,3,2] row_mask:0xf bank_mask:0xf
	s_nop 1
	v_add_f32_dpp v110, v110, v110 quad_perm:[2,3,0,1] row_mask:0xf bank_mask:0xf
	s_nop 1
	v_add_f32_dpp v110, v110, v110 row_half_mirror row_mask:0xf bank_mask:0xf
	s_nop 1
	v_add_f32_dpp v110, v110, v110 row_mirror row_mask:0xf bank_mask:0xf
	v_add_f32_e32 v110, 0x358637bd, v110
	v_rsq_f32_e32 v110, v110
	s_nop 0
	v_mul_f32_e32 v110, v44, v110
	v_pk_mul_f32 v[96:97], v[96:97], v[110:111] op_sel_hi:[1,0]
	v_pk_mul_f32 v[94:95], v[94:95], v[110:111] op_sel_hi:[1,0]
	v_pk_mul_f32 v[98:99], v[98:99], v[110:111] op_sel_hi:[1,0]
	v_pk_mul_f32 v[100:101], v[100:101], v[110:111] op_sel_hi:[1,0]
